# conv epilogue: packed f32 ops for the centre tap and the SiLU arithmetic (pure-VALU epilogue, fewer issue slots)
# speedup vs baseline: 1.1046x; 1.0090x over previous
.Lce_edge_done:
	s_lshl_b32 s4, s98, 11
	s_add_i32 s4, s4, 0x20800
	s_mov_b32 exec_lo, 0x10001
	s_mov_b32 exec_hi, 0x10001
	v_lshl_add_u32 v221, v220, 2, s4
	ds_write_b128 v221, v[160:163] offset:0
	ds_write_b128 v221, v[64:67] offset:16
	ds_write_b128 v221, v[156:159] offset:512
	ds_write_b128 v221, v[60:63] offset:528
	ds_write_b128 v221, v[96:99] offset:4096
	ds_write_b128 v221, v[32:35] offset:4112
	ds_write_b128 v221, v[92:95] offset:4608
	ds_write_b128 v221, v[28:31] offset:4624
	s_mov_b32 exec_lo, 0x80008000
	s_mov_b32 exec_hi, 0x80008000
	v_lshl_add_u32 v221, v220, 2, s4
	ds_write_b128 v221, v[100:103] offset:1024
	ds_write_b128 v221, v[36:39] offset:1040
	ds_write_b128 v221, v[104:107] offset:1536
	ds_write_b128 v221, v[40:43] offset:1552
	ds_write_b128 v221, v[68:71] offset:5120
	ds_write_b128 v221, v[4:7] offset:5136
	ds_write_b128 v221, v[72:75] offset:5632
	ds_write_b128 v221, v[8:11] offset:5648
	s_mov_b64 exec, -1
	v_lshl_add_u32 v221, v220, 2, s4
	s_lshl_b32 s5, s98, 10
	v_subrev_u32_e32 v222, s5, v221
	s_sub_i32 s5, 0x1800, s5
	v_add_u32_e32 v223, s5, v221
	v_mul_u32_u24_e32 v244, 0x1600, v242
	v_lshl_add_u32 v244, v220, 1, v244
	s_lshl_b32 s4, s18, 8
	s_lshl_b32 s5, s98, 6
	s_add_i32 s4, s4, s5
	s_mul_i32 s4, s4, 0x1600
	s_lshl_b32 s5, s14, 8
	s_add_u32 s4, s4, s5
	v_readlane_b32 s6, v251, 12
	v_readlane_b32 s7, v251, 13
	s_nop 1
	s_add_u32 s6, s6, s4
	s_addc_u32 s7, s7, 0
	v_mov_b32_e32 v224, 0xbfb8aa3b
	s_waitcnt lgkmcnt(0)
	s_barrier
	s_cmp_eq_u32 s98, 0
	s_cbranch_scc0 .Lce_nobar0
	s_barrier
.Lce_nobar0:
	ds_read_b128 v[164:167], v222 offset:0
	ds_read_b128 v[168:171], v222 offset:512
	s_waitcnt vmcnt(4)
	v_pk_fma_f32 v[208:209], v[120:121], v[152:153], v[128:129]
	v_pk_fma_f32 v[210:211], v[122:123], v[154:155], v[130:131]
	v_fmac_f32_dpp v208, v152, v116 row_shr:1 row_mask:0xf bank_mask:0xf
	v_fmac_f32_dpp v209, v153, v117 row_shr:1 row_mask:0xf bank_mask:0xf
	v_fmac_f32_dpp v210, v154, v118 row_shr:1 row_mask:0xf bank_mask:0xf
	v_fmac_f32_dpp v211, v155, v119 row_shr:1 row_mask:0xf bank_mask:0xf
	v_fmac_f32_dpp v208, v152, v124 row_shl:1 row_mask:0xf bank_mask:0xf
	v_fmac_f32_dpp v209, v153, v125 row_shl:1 row_mask:0xf bank_mask:0xf
	v_fmac_f32_dpp v210, v154, v126 row_shl:1 row_mask:0xf bank_mask:0xf
	v_fmac_f32_dpp v211, v155, v127 row_shl:1 row_mask:0xf bank_mask:0xf
	v_fmac_f32_dpp v208, v160, v116 row_shl:15 row_mask:0xf bank_mask:0xf
	v_fmac_f32_dpp v209, v161, v117 row_shl:15 row_mask:0xf bank_mask:0xf
	v_fmac_f32_dpp v210, v162, v118 row_shl:15 row_mask:0xf bank_mask:0xf
	v_fmac_f32_dpp v211, v163, v119 row_shl:15 row_mask:0xf bank_mask:0xf
	v_fmac_f32_dpp v208, v112, v124 row_shr:15 row_mask:0xf bank_mask:0xf
	v_fmac_f32_dpp v209, v113, v125 row_shr:15 row_mask:0xf bank_mask:0xf
	v_fmac_f32_dpp v210, v114, v126 row_shr:15 row_mask:0xf bank_mask:0xf
	v_fmac_f32_dpp v211, v115, v127 row_shr:15 row_mask:0xf bank_mask:0xf
	v_pk_fma_f32 v[212:213], v[136:137], v[148:149], v[144:145]
	v_pk_fma_f32 v[214:215], v[138:139], v[150:151], v[146:147]
	v_fmac_f32_dpp v212, v148, v132 row_shr:1 row_mask:0xf bank_mask:0xf
	v_fmac_f32_dpp v213, v149, v133 row_shr:1 row_mask:0xf bank_mask:0xf
	v_fmac_f32_dpp v214, v150, v134 row_shr:1 row_mask:0xf bank_mask:0xf
	v_fmac_f32_dpp v215, v151, v135 row_shr:1 row_mask:0xf bank_mask:0xf
	v_fmac_f32_dpp v212, v148, v140 row_shl:1 row_mask:0xf bank_mask:0xf
	v_fmac_f32_dpp v213, v149, v141 row_shl:1 row_mask:0xf bank_mask:0xf
	v_fmac_f32_dpp v214, v150, v142 row_shl:1 row_mask:0xf bank_mask:0xf
	v_fmac_f32_dpp v215, v151, v143 row_shl:1 row_mask:0xf bank_mask:0xf
	v_fmac_f32_dpp v212, v156, v132 row_shl:15 row_mask:0xf bank_mask:0xf
	v_fmac_f32_dpp v213, v157, v133 row_shl:15 row_mask:0xf bank_mask:0xf
	v_fmac_f32_dpp v214, v158, v134 row_shl:15 row_mask:0xf bank_mask:0xf
	v_fmac_f32_dpp v215, v159, v135 row_shl:15 row_mask:0xf bank_mask:0xf
	v_fmac_f32_dpp v212, v108, v140 row_shr:15 row_mask:0xf bank_mask:0xf
	v_fmac_f32_dpp v213, v109, v141 row_shr:15 row_mask:0xf bank_mask:0xf
	v_fmac_f32_dpp v214, v110, v142 row_shr:15 row_mask:0xf bank_mask:0xf
	v_fmac_f32_dpp v215, v111, v143 row_shr:15 row_mask:0xf bank_mask:0xf
	v_pk_mul_f32 v[216:217], v[208:209], v[224:225] op_sel_hi:[1,0]
	v_pk_mul_f32 v[218:219], v[210:211], v[224:225] op_sel_hi:[1,0]
	v_exp_f32_e32 v216, v216
	v_exp_f32_e32 v217, v217
	v_exp_f32_e32 v218, v218
	v_exp_f32_e32 v219, v219
	v_pk_add_f32 v[216:217], v[216:217], 1.0 op_sel_hi:[1,0]
	v_pk_add_f32 v[218:219], v[218:219], 1.0 op_sel_hi:[1,0]
	v_rcp_f32_e32 v216, v216
	v_rcp_f32_e32 v217, v217
	v_rcp_f32_e32 v218, v218
	v_rcp_f32_e32 v219, v219
	v_pk_mul_f32 v[208:209], v[208:209], v[216:217]
	v_pk_mul_f32 v[210:211], v[210:211], v[218:219]
	v_pk_mul_f32 v[208:209], v[208:209], v[212:213]
	v_pk_mul_f32 v[210:211], v[210:211], v[214:215]
	v_cvt_pk_bf16_f32 v174, v208, v209
	v_cvt_pk_bf16_f32 v175, v210, v211
	v_pk_fma_f32 v[208:209], v[120:121], v[112:113], v[128:129]
	v_pk_fma_f32 v[210:211], v[122:123], v[114:115], v[130:131]
	v_fmac_f32_dpp v208, v112, v116 row_shr:1 row_mask:0xf bank_mask:0xf
	v_fmac_f32_dpp v209, v113, v117 row_shr:1 row_mask:0xf bank_mask:0xf
	v_fmac_f32_dpp v210, v114, v118 row_shr:1 row_mask:0xf bank_mask:0xf
	v_fmac_f32_dpp v211, v115, v119 row_shr:1 row_mask:0xf bank_mask:0xf
	v_fmac_f32_dpp v208, v112, v124 row_shl:1 row_mask:0xf bank_mask:0xf
	v_fmac_f32_dpp v209, v113, v125 row_shl:1 row_mask:0xf bank_mask:0xf
	v_fmac_f32_dpp v210, v114, v126 row_shl:1 row_mask:0xf bank_mask:0xf
	v_fmac_f32_dpp v211, v115, v127 row_shl:1 row_mask:0xf bank_mask:0xf
	v_fmac_f32_dpp v208, v152, v116 row_shl:15 row_mask:0xf bank_mask:0xf
	v_fmac_f32_dpp v209, v153, v117 row_shl:15 row_mask:0xf bank_mask:0xf
	v_fmac_f32_dpp v210, v154, v118 row_shl:15 row_mask:0xf bank_mask:0xf
	v_fmac_f32_dpp v211, v155, v119 row_shl:15 row_mask:0xf bank_mask:0xf
	v_fmac_f32_dpp v208, v100, v124 row_shr:15 row_mask:0xf bank_mask:0xf
	v_fmac_f32_dpp v209, v101, v125 row_shr:15 row_mask:0xf bank_mask:0xf
	v_fmac_f32_dpp v210, v102, v126 row_shr:15 row_mask:0xf bank_mask:0xf
	v_fmac_f32_dpp v211, v103, v127 row_shr:15 row_mask:0xf bank_mask:0xf
	v_pk_fma_f32 v[212:213], v[136:137], v[108:109], v[144:145]
	v_pk_fma_f32 v[214:215], v[138:139], v[110:111], v[146:147]
	v_fmac_f32_dpp v212, v108, v132 row_shr:1 row_mask:0xf bank_mask:0xf
	v_fmac_f32_dpp v213, v109, v133 row_shr:1 row_mask:0xf bank_mask:0xf
	v_fmac_f32_dpp v214, v110, v134 row_shr:1 row_mask:0xf bank_mask:0xf
	v_fmac_f32_dpp v215, v111, v135 row_shr:1 row_mask:0xf bank_mask:0xf
	v_fmac_f32_dpp v212, v108, v140 row_shl:1 row_mask:0xf bank_mask:0xf
	v_fmac_f32_dpp v213, v109, v141 row_shl:1 row_mask:0xf bank_mask:0xf
	v_fmac_f32_dpp v214, v110, v142 row_shl:1 row_mask:0xf bank_mask:0xf
	v_fmac_f32_dpp v215, v111, v143 row_shl:1 row_mask:0xf bank_mask:0xf
	v_fmac_f32_dpp v212, v148, v132 row_shl:15 row_mask:0xf bank_mask:0xf
	v_fmac_f32_dpp v213, v149, v133 row_shl:15 row_mask:0xf bank_mask:0xf
	v_fmac_f32_dpp v214, v150, v134 row_shl:15 row_mask:0xf bank_mask:0xf
	v_fmac_f32_dpp v215, v151, v135 row_shl:15 row_mask:0xf bank_mask:0xf
	v_fmac_f32_dpp v212, v104, v140 row_shr:15 row_mask:0xf bank_mask:0xf
	v_fmac_f32_dpp v213, v105, v141 row_shr:15 row_mask:0xf bank_mask:0xf
	v_fmac_f32_dpp v214, v106, v142 row_shr:15 row_mask:0xf bank_mask:0xf
	v_fmac_f32_dpp v215, v107, v143 row_shr:15 row_mask:0xf bank_mask:0xf
	v_pk_mul_f32 v[216:217], v[208:209], v[224:225] op_sel_hi:[1,0]
	v_pk_mul_f32 v[218:219], v[210:211], v[224:225] op_sel_hi:[1,0]
	v_exp_f32_e32 v216, v216
	v_exp_f32_e32 v217, v217
	v_exp_f32_e32 v218, v218
	v_exp_f32_e32 v219, v219
	v_pk_add_f32 v[216:217], v[216:217], 1.0 op_sel_hi:[1,0]
	v_pk_add_f32 v[218:219], v[218:219], 1.0 op_sel_hi:[1,0]
	v_rcp_f32_e32 v216, v216
	v_rcp_f32_e32 v217, v217
	v_rcp_f32_e32 v218, v218
	v_rcp_f32_e32 v219, v219
	v_pk_mul_f32 v[208:209], v[208:209], v[216:217]
	v_pk_mul_f32 v[210:211], v[210:211], v[218:219]
	v_pk_mul_f32 v[208:209], v[208:209], v[212:213]
	v_pk_mul_f32 v[210:211], v[210:211], v[214:215]
	v_cvt_pk_bf16_f32 v176, v208, v209
	v_cvt_pk_bf16_f32 v177, v210, v211
	s_waitcnt lgkmcnt(0)
	v_pk_fma_f32 v[208:209], v[120:121], v[160:161], v[128:129]
	v_pk_fma_f32 v[210:211], v[122:123], v[162:163], v[130:131]
	v_fmac_f32_dpp v208, v160, v116 row_shr:1 row_mask:0xf bank_mask:0xf
	v_fmac_f32_dpp v209, v161, v117 row_shr:1 row_mask:0xf bank_mask:0xf
	v_fmac_f32_dpp v210, v162, v118 row_shr:1 row_mask:0xf bank_mask:0xf
	v_fmac_f32_dpp v211, v163, v119 row_shr:1 row_mask:0xf bank_mask:0xf
	v_fmac_f32_dpp v208, v160, v124 row_shl:1 row_mask:0xf bank_mask:0xf
	v_fmac_f32_dpp v209, v161, v125 row_shl:1 row_mask:0xf bank_mask:0xf
	v_fmac_f32_dpp v210, v162, v126 row_shl:1 row_mask:0xf bank_mask:0xf
	v_fmac_f32_dpp v211, v163, v127 row_shl:1 row_mask:0xf bank_mask:0xf
	v_fmac_f32_dpp v208, v164, v116 row_shl:15 row_mask:0xf bank_mask:0xf
	v_fmac_f32_dpp v209, v165, v117 row_shl:15 row_mask:0xf bank_mask:0xf
	v_fmac_f32_dpp v210, v166, v118 row_shl:15 row_mask:0xf bank_mask:0xf
	v_fmac_f32_dpp v211, v167, v119 row_shl:15 row_mask:0xf bank_mask:0xf
	v_fmac_f32_dpp v208, v152, v124 row_shr:15 row_mask:0xf bank_mask:0xf
	v_fmac_f32_dpp v209, v153, v125 row_shr:15 row_mask:0xf bank_mask:0xf
	v_fmac_f32_dpp v210, v154, v126 row_shr:15 row_mask:0xf bank_mask:0xf
	v_fmac_f32_dpp v211, v155, v127 row_shr:15 row_mask:0xf bank_mask:0xf
	v_pk_fma_f32 v[212:213], v[136:137], v[156:157], v[144:145]
	v_pk_fma_f32 v[214:215], v[138:139], v[158:159], v[146:147]
	v_fmac_f32_dpp v212, v156, v132 row_shr:1 row_mask:0xf bank_mask:0xf
	v_fmac_f32_dpp v213, v157, v133 row_shr:1 row_mask:0xf bank_mask:0xf
	v_fmac_f32_dpp v214, v158, v134 row_shr:1 row_mask:0xf bank_mask:0xf
	v_fmac_f32_dpp v215, v159, v135 row_shr:1 row_mask:0xf bank_mask:0xf
	v_fmac_f32_dpp v212, v156, v140 row_shl:1 row_mask:0xf bank_mask:0xf
	v_fmac_f32_dpp v213, v157, v141 row_shl:1 row_mask:0xf bank_mask:0xf
	v_fmac_f32_dpp v214, v158, v142 row_shl:1 row_mask:0xf bank_mask:0xf
	v_fmac_f32_dpp v215, v159, v143 row_shl:1 row_mask:0xf bank_mask:0xf
	v_fmac_f32_dpp v212, v168, v132 row_shl:15 row_mask:0xf bank_mask:0xf
	v_fmac_f32_dpp v213, v169, v133 row_shl:15 row_mask:0xf bank_mask:0xf
	v_fmac_f32_dpp v214, v170, v134 row_shl:15 row_mask:0xf bank_mask:0xf
	v_fmac_f32_dpp v215, v171, v135 row_shl:15 row_mask:0xf bank_mask:0xf
	v_fmac_f32_dpp v212, v148, v140 row_shr:15 row_mask:0xf bank_mask:0xf
	v_fmac_f32_dpp v213, v149, v141 row_shr:15 row_mask:0xf bank_mask:0xf
	v_fmac_f32_dpp v214, v150, v142 row_shr:15 row_mask:0xf bank_mask:0xf
	v_fmac_f32_dpp v215, v151, v143 row_shr:15 row_mask:0xf bank_mask:0xf
	ds_read_b128 v[164:167], v221 offset:2048
	ds_read_b128 v[168:171], v221 offset:2560
	v_pk_mul_f32 v[216:217], v[208:209], v[224:225] op_sel_hi:[1,0]
	v_pk_mul_f32 v[218:219], v[210:211], v[224:225] op_sel_hi:[1,0]
	v_exp_f32_e32 v216, v216
	v_exp_f32_e32 v217, v217
	v_exp_f32_e32 v218, v218
	v_exp_f32_e32 v219, v219
	v_pk_add_f32 v[216:217], v[216:217], 1.0 op_sel_hi:[1,0]
	v_pk_add_f32 v[218:219], v[218:219], 1.0 op_sel_hi:[1,0]
	v_rcp_f32_e32 v216, v216
	v_rcp_f32_e32 v217, v217
	v_rcp_f32_e32 v218, v218
	v_rcp_f32_e32 v219, v219
	v_pk_mul_f32 v[208:209], v[208:209], v[216:217]
	v_pk_mul_f32 v[210:211], v[210:211], v[218:219]
	v_pk_mul_f32 v[208:209], v[208:209], v[212:213]
	v_pk_mul_f32 v[210:211], v[210:211], v[214:215]
	v_cvt_pk_bf16_f32 v172, v208, v209
	v_cvt_pk_bf16_f32 v173, v210, v211
	s_waitcnt lgkmcnt(0)
	v_pk_fma_f32 v[208:209], v[120:121], v[100:101], v[128:129]
	v_pk_fma_f32 v[210:211], v[122:123], v[102:103], v[130:131]
	v_fmac_f32_dpp v208, v100, v116 row_shr:1 row_mask:0xf bank_mask:0xf
	v_fmac_f32_dpp v209, v101, v117 row_shr:1 row_mask:0xf bank_mask:0xf
	v_fmac_f32_dpp v210, v102, v118 row_shr:1 row_mask:0xf bank_mask:0xf
	v_fmac_f32_dpp v211, v103, v119 row_shr:1 row_mask:0xf bank_mask:0xf
	v_fmac_f32_dpp v208, v100, v124 row_shl:1 row_mask:0xf bank_mask:0xf
	v_fmac_f32_dpp v209, v101, v125 row_shl:1 row_mask:0xf bank_mask:0xf
	v_fmac_f32_dpp v210, v102, v126 row_shl:1 row_mask:0xf bank_mask:0xf
	v_fmac_f32_dpp v211, v103, v127 row_shl:1 row_mask:0xf bank_mask:0xf
	v_fmac_f32_dpp v208, v112, v116 row_shl:15 row_mask:0xf bank_mask:0xf
	v_fmac_f32_dpp v209, v113, v117 row_shl:15 row_mask:0xf bank_mask:0xf
	v_fmac_f32_dpp v210, v114, v118 row_shl:15 row_mask:0xf bank_mask:0xf
	v_fmac_f32_dpp v211, v115, v119 row_shl:15 row_mask:0xf bank_mask:0xf
	v_fmac_f32_dpp v208, v164, v124 row_shr:15 row_mask:0xf bank_mask:0xf
	v_fmac_f32_dpp v209, v165, v125 row_shr:15 row_mask:0xf bank_mask:0xf
	v_fmac_f32_dpp v210, v166, v126 row_shr:15 row_mask:0xf bank_mask:0xf
	v_fmac_f32_dpp v211, v167, v127 row_shr:15 row_mask:0xf bank_mask:0xf
	v_pk_fma_f32 v[212:213], v[136:137], v[104:105], v[144:145]
	v_pk_fma_f32 v[214:215], v[138:139], v[106:107], v[146:147]
	v_fmac_f32_dpp v212, v104, v132 row_shr:1 row_mask:0xf bank_mask:0xf
	v_fmac_f32_dpp v213, v105, v133 row_shr:1 row_mask:0xf bank_mask:0xf
	v_fmac_f32_dpp v214, v106, v134 row_shr:1 row_mask:0xf bank_mask:0xf
	v_fmac_f32_dpp v215, v107, v135 row_shr:1 row_mask:0xf bank_mask:0xf
	v_fmac_f32_dpp v212, v104, v140 row_shl:1 row_mask:0xf bank_mask:0xf
	v_fmac_f32_dpp v213, v105, v141 row_shl:1 row_mask:0xf bank_mask:0xf
	v_fmac_f32_dpp v214, v106, v142 row_shl:1 row_mask:0xf bank_mask:0xf
	v_fmac_f32_dpp v215, v107, v143 row_shl:1 row_mask:0xf bank_mask:0xf
	v_fmac_f32_dpp v212, v108, v132 row_shl:15 row_mask:0xf bank_mask:0xf
	v_fmac_f32_dpp v213, v109, v133 row_shl:15 row_mask:0xf bank_mask:0xf
	v_fmac_f32_dpp v214, v110, v134 row_shl:15 row_mask:0xf bank_mask:0xf
	v_fmac_f32_dpp v215, v111, v135 row_shl:15 row_mask:0xf bank_mask:0xf
	v_fmac_f32_dpp v212, v168, v140 row_shr:15 row_mask:0xf bank_mask:0xf
	v_fmac_f32_dpp v213, v169, v141 row_shr:15 row_mask:0xf bank_mask:0xf
	v_fmac_f32_dpp v214, v170, v142 row_shr:15 row_mask:0xf bank_mask:0xf
	v_fmac_f32_dpp v215, v171, v143 row_shr:15 row_mask:0xf bank_mask:0xf
	v_pk_mul_f32 v[216:217], v[208:209], v[224:225] op_sel_hi:[1,0]
	v_pk_mul_f32 v[218:219], v[210:211], v[224:225] op_sel_hi:[1,0]
	v_exp_f32_e32 v216, v216
	v_exp_f32_e32 v217, v217
	v_exp_f32_e32 v218, v218
	v_exp_f32_e32 v219, v219
	v_pk_add_f32 v[216:217], v[216:217], 1.0 op_sel_hi:[1,0]
	v_pk_add_f32 v[218:219], v[218:219], 1.0 op_sel_hi:[1,0]
	v_rcp_f32_e32 v216, v216
	v_rcp_f32_e32 v217, v217
	v_rcp_f32_e32 v218, v218
	v_rcp_f32_e32 v219, v219
	v_pk_mul_f32 v[208:209], v[208:209], v[216:217]
	v_pk_mul_f32 v[210:211], v[210:211], v[218:219]
	v_pk_mul_f32 v[208:209], v[208:209], v[212:213]
	v_pk_mul_f32 v[210:211], v[210:211], v[214:215]
	v_cvt_pk_bf16_f32 v178, v208, v209
	v_cvt_pk_bf16_f32 v179, v210, v211
	v_readlane_b32 s10, v250, 7
	v_readlane_b32 s11, v250, 8
	v_readlane_b32 s100, v250, 9
	v_readlane_b32 s101, v250, 10
	s_nop 1
	s_add_u32 s12, s10, 0x5800
	s_addc_u32 s13, s11, 0
	s_add_u32 s4, s10, 0xb000
	s_addc_u32 s5, s11, 0
	s_nop 2
	global_load_dwordx4 v[160:163], v245, s[10:11] offset:16
	global_load_dwordx4 v[152:155], v245, s[12:13] offset:16
	global_load_dwordx4 v[112:115], v245, s[4:5] offset:16
	global_load_dwordx4 v[100:103], v245, s[100:101] offset:16
	global_load_dwordx4 v[156:159], v246, s[10:11] offset:16
	global_load_dwordx4 v[148:151], v246, s[12:13] offset:16
	global_load_dwordx4 v[108:111], v246, s[4:5] offset:16
	global_load_dwordx4 v[104:107], v246, s[100:101] offset:16
	ds_read_b128 v[164:167], v221 offset:3072
	ds_read_b128 v[168:171], v221 offset:3584
	v_pk_fma_f32 v[208:209], v[120:121], v[88:89], v[128:129]
	v_pk_fma_f32 v[210:211], v[122:123], v[90:91], v[130:131]
	v_fmac_f32_dpp v208, v88, v116 row_shr:1 row_mask:0xf bank_mask:0xf
	v_fmac_f32_dpp v209, v89, v117 row_shr:1 row_mask:0xf bank_mask:0xf
	v_fmac_f32_dpp v210, v90, v118 row_shr:1 row_mask:0xf bank_mask:0xf
	v_fmac_f32_dpp v211, v91, v119 row_shr:1 row_mask:0xf bank_mask:0xf
	v_fmac_f32_dpp v208, v88, v124 row_shl:1 row_mask:0xf bank_mask:0xf
	v_fmac_f32_dpp v209, v89, v125 row_shl:1 row_mask:0xf bank_mask:0xf
	v_fmac_f32_dpp v210, v90, v126 row_shl:1 row_mask:0xf bank_mask:0xf
	v_fmac_f32_dpp v211, v91, v127 row_shl:1 row_mask:0xf bank_mask:0xf
	v_fmac_f32_dpp v208, v96, v116 row_shl:15 row_mask:0xf bank_mask:0xf
	v_fmac_f32_dpp v209, v97, v117 row_shl:15 row_mask:0xf bank_mask:0xf
	v_fmac_f32_dpp v210, v98, v118 row_shl:15 row_mask:0xf bank_mask:0xf
	v_fmac_f32_dpp v211, v99, v119 row_shl:15 row_mask:0xf bank_mask:0xf
	v_fmac_f32_dpp v208, v80, v124 row_shr:15 row_mask:0xf bank_mask:0xf
	v_fmac_f32_dpp v209, v81, v125 row_shr:15 row_mask:0xf bank_mask:0xf
	v_fmac_f32_dpp v210, v82, v126 row_shr:15 row_mask:0xf bank_mask:0xf
	v_fmac_f32_dpp v211, v83, v127 row_shr:15 row_mask:0xf bank_mask:0xf
	v_pk_fma_f32 v[212:213], v[136:137], v[84:85], v[144:145]
	v_pk_fma_f32 v[214:215], v[138:139], v[86:87], v[146:147]
	v_fmac_f32_dpp v212, v84, v132 row_shr:1 row_mask:0xf bank_mask:0xf
	v_fmac_f32_dpp v213, v85, v133 row_shr:1 row_mask:0xf bank_mask:0xf
	v_fmac_f32_dpp v214, v86, v134 row_shr:1 row_mask:0xf bank_mask:0xf
	v_fmac_f32_dpp v215, v87, v135 row_shr:1 row_mask:0xf bank_mask:0xf
	v_fmac_f32_dpp v212, v84, v140 row_shl:1 row_mask:0xf bank_mask:0xf
	v_fmac_f32_dpp v213, v85, v141 row_shl:1 row_mask:0xf bank_mask:0xf
	v_fmac_f32_dpp v214, v86, v142 row_shl:1 row_mask:0xf bank_mask:0xf
	v_fmac_f32_dpp v215, v87, v143 row_shl:1 row_mask:0xf bank_mask:0xf
	v_fmac_f32_dpp v212, v92, v132 row_shl:15 row_mask:0xf bank_mask:0xf
	v_fmac_f32_dpp v213, v93, v133 row_shl:15 row_mask:0xf bank_mask:0xf
	v_fmac_f32_dpp v214, v94, v134 row_shl:15 row_mask:0xf bank_mask:0xf
	v_fmac_f32_dpp v215, v95, v135 row_shl:15 row_mask:0xf bank_mask:0xf
	v_fmac_f32_dpp v212, v76, v140 row_shr:15 row_mask:0xf bank_mask:0xf
	v_fmac_f32_dpp v213, v77, v141 row_shr:15 row_mask:0xf bank_mask:0xf
	v_fmac_f32_dpp v214, v78, v142 row_shr:15 row_mask:0xf bank_mask:0xf
	v_fmac_f32_dpp v215, v79, v143 row_shr:15 row_mask:0xf bank_mask:0xf
	v_pk_mul_f32 v[216:217], v[208:209], v[224:225] op_sel_hi:[1,0]
	v_pk_mul_f32 v[218:219], v[210:211], v[224:225] op_sel_hi:[1,0]
	v_exp_f32_e32 v216, v216
	v_exp_f32_e32 v217, v217
	v_exp_f32_e32 v218, v218
	v_exp_f32_e32 v219, v219
	v_pk_add_f32 v[216:217], v[216:217], 1.0 op_sel_hi:[1,0]
	v_pk_add_f32 v[218:219], v[218:219], 1.0 op_sel_hi:[1,0]
	v_rcp_f32_e32 v216, v216
	v_rcp_f32_e32 v217, v217
	v_rcp_f32_e32 v218, v218
	v_rcp_f32_e32 v219, v219
	v_pk_mul_f32 v[208:209], v[208:209], v[216:217]
	v_pk_mul_f32 v[210:211], v[210:211], v[218:219]
	v_pk_mul_f32 v[208:209], v[208:209], v[212:213]
	v_pk_mul_f32 v[210:211], v[210:211], v[214:215]
	v_cvt_pk_bf16_f32 v247, v208, v209
	v_cvt_pk_bf16_f32 v248, v210, v211
	v_pk_fma_f32 v[208:209], v[120:121], v[80:81], v[128:129]
	v_pk_fma_f32 v[210:211], v[122:123], v[82:83], v[130:131]
	v_fmac_f32_dpp v208, v80, v116 row_shr:1 row_mask:0xf bank_mask:0xf
	v_fmac_f32_dpp v209, v81, v117 row_shr:1 row_mask:0xf bank_mask:0xf
	v_fmac_f32_dpp v210, v82, v118 row_shr:1 row_mask:0xf bank_mask:0xf
	v_fmac_f32_dpp v211, v83, v119 row_shr:1 row_mask:0xf bank_mask:0xf
	v_fmac_f32_dpp v208, v80, v124 row_shl:1 row_mask:0xf bank_mask:0xf
	v_fmac_f32_dpp v209, v81, v125 row_shl:1 row_mask:0xf bank_mask:0xf
	v_fmac_f32_dpp v210, v82, v126 row_shl:1 row_mask:0xf bank_mask:0xf
	v_fmac_f32_dpp v211, v83, v127 row_shl:1 row_mask:0xf bank_mask:0xf
	v_fmac_f32_dpp v208, v88, v116 row_shl:15 row_mask:0xf bank_mask:0xf
	v_fmac_f32_dpp v209, v89, v117 row_shl:15 row_mask:0xf bank_mask:0xf
	v_fmac_f32_dpp v210, v90, v118 row_shl:15 row_mask:0xf bank_mask:0xf
	v_fmac_f32_dpp v211, v91, v119 row_shl:15 row_mask:0xf bank_mask:0xf
	v_fmac_f32_dpp v208, v68, v124 row_shr:15 row_mask:0xf bank_mask:0xf
	v_fmac_f32_dpp v209, v69, v125 row_shr:15 row_mask:0xf bank_mask:0xf
	v_fmac_f32_dpp v210, v70, v126 row_shr:15 row_mask:0xf bank_mask:0xf
	v_fmac_f32_dpp v211, v71, v127 row_shr:15 row_mask:0xf bank_mask:0xf
	v_pk_fma_f32 v[212:213], v[136:137], v[76:77], v[144:145]
	v_pk_fma_f32 v[214:215], v[138:139], v[78:79], v[146:147]
	v_fmac_f32_dpp v212, v76, v132 row_shr:1 row_mask:0xf bank_mask:0xf
	v_fmac_f32_dpp v213, v77, v133 row_shr:1 row_mask:0xf bank_mask:0xf
	v_fmac_f32_dpp v214, v78, v134 row_shr:1 row_mask:0xf bank_mask:0xf
	v_fmac_f32_dpp v215, v79, v135 row_shr:1 row_mask:0xf bank_mask:0xf
	v_fmac_f32_dpp v212, v76, v140 row_shl:1 row_mask:0xf bank_mask:0xf
	v_fmac_f32_dpp v213, v77, v141 row_shl:1 row_mask:0xf bank_mask:0xf
	v_fmac_f32_dpp v214, v78, v142 row_shl:1 row_mask:0xf bank_mask:0xf
	v_fmac_f32_dpp v215, v79, v143 row_shl:1 row_mask:0xf bank_mask:0xf
	v_fmac_f32_dpp v212, v84, v132 row_shl:15 row_mask:0xf bank_mask:0xf
	v_fmac_f32_dpp v213, v85, v133 row_shl:15 row_mask:0xf bank_mask:0xf
	v_fmac_f32_dpp v214, v86, v134 row_shl:15 row_mask:0xf bank_mask:0xf
	v_fmac_f32_dpp v215, v87, v135 row_shl:15 row_mask:0xf bank_mask:0xf
	v_fmac_f32_dpp v212, v72, v140 row_shr:15 row_mask:0xf bank_mask:0xf
	v_fmac_f32_dpp v213, v73, v141 row_shr:15 row_mask:0xf bank_mask:0xf
	v_fmac_f32_dpp v214, v74, v142 row_shr:15 row_mask:0xf bank_mask:0xf
	v_fmac_f32_dpp v215, v75, v143 row_shr:15 row_mask:0xf bank_mask:0xf
	v_pk_mul_f32 v[216:217], v[208:209], v[224:225] op_sel_hi:[1,0]
	v_pk_mul_f32 v[218:219], v[210:211], v[224:225] op_sel_hi:[1,0]
	v_exp_f32_e32 v216, v216
	v_exp_f32_e32 v217, v217
	v_exp_f32_e32 v218, v218
	v_exp_f32_e32 v219, v219
	v_pk_add_f32 v[216:217], v[216:217], 1.0 op_sel_hi:[1,0]
	v_pk_add_f32 v[218:219], v[218:219], 1.0 op_sel_hi:[1,0]
	v_rcp_f32_e32 v216, v216
	v_rcp_f32_e32 v217, v217
	v_rcp_f32_e32 v218, v218
	v_rcp_f32_e32 v219, v219
	v_pk_mul_f32 v[208:209], v[208:209], v[216:217]
	v_pk_mul_f32 v[210:211], v[210:211], v[218:219]
	v_pk_mul_f32 v[208:209], v[208:209], v[212:213]
	v_pk_mul_f32 v[210:211], v[210:211], v[214:215]
	v_cvt_pk_bf16_f32 v249, v208, v209
	v_cvt_pk_bf16_f32 v2, v210, v211
	s_waitcnt lgkmcnt(0)
	v_pk_fma_f32 v[208:209], v[120:121], v[96:97], v[128:129]
	v_pk_fma_f32 v[210:211], v[122:123], v[98:99], v[130:131]
	v_fmac_f32_dpp v208, v96, v116 row_shr:1 row_mask:0xf bank_mask:0xf
	v_fmac_f32_dpp v209, v97, v117 row_shr:1 row_mask:0xf bank_mask:0xf
	v_fmac_f32_dpp v210, v98, v118 row_shr:1 row_mask:0xf bank_mask:0xf
	v_fmac_f32_dpp v211, v99, v119 row_shr:1 row_mask:0xf bank_mask:0xf
	v_fmac_f32_dpp v208, v96, v124 row_shl:1 row_mask:0xf bank_mask:0xf
	v_fmac_f32_dpp v209, v97, v125 row_shl:1 row_mask:0xf bank_mask:0xf
	v_fmac_f32_dpp v210, v98, v126 row_shl:1 row_mask:0xf bank_mask:0xf
	v_fmac_f32_dpp v211, v99, v127 row_shl:1 row_mask:0xf bank_mask:0xf
	v_fmac_f32_dpp v208, v164, v116 row_shl:15 row_mask:0xf bank_mask:0xf
	v_fmac_f32_dpp v209, v165, v117 row_shl:15 row_mask:0xf bank_mask:0xf
	v_fmac_f32_dpp v210, v166, v118 row_shl:15 row_mask:0xf bank_mask:0xf
	v_fmac_f32_dpp v211, v167, v119 row_shl:15 row_mask:0xf bank_mask:0xf
	v_fmac_f32_dpp v208, v88, v124 row_shr:15 row_mask:0xf bank_mask:0xf
	v_fmac_f32_dpp v209, v89, v125 row_shr:15 row_mask:0xf bank_mask:0xf
	v_fmac_f32_dpp v210, v90, v126 row_shr:15 row_mask:0xf bank_mask:0xf
	v_fmac_f32_dpp v211, v91, v127 row_shr:15 row_mask:0xf bank_mask:0xf
	v_pk_fma_f32 v[212:213], v[136:137], v[92:93], v[144:145]
	v_pk_fma_f32 v[214:215], v[138:139], v[94:95], v[146:147]
	v_fmac_f32_dpp v212, v92, v132 row_shr:1 row_mask:0xf bank_mask:0xf
	v_fmac_f32_dpp v213, v93, v133 row_shr:1 row_mask:0xf bank_mask:0xf
	v_fmac_f32_dpp v214, v94, v134 row_shr:1 row_mask:0xf bank_mask:0xf
	v_fmac_f32_dpp v215, v95, v135 row_shr:1 row_mask:0xf bank_mask:0xf
	v_fmac_f32_dpp v212, v92, v140 row_shl:1 row_mask:0xf bank_mask:0xf
	v_fmac_f32_dpp v213, v93, v141 row_shl:1 row_mask:0xf bank_mask:0xf
	v_fmac_f32_dpp v214, v94, v142 row_shl:1 row_mask:0xf bank_mask:0xf
	v_fmac_f32_dpp v215, v95, v143 row_shl:1 row_mask:0xf bank_mask:0xf
	v_fmac_f32_dpp v212, v168, v132 row_shl:15 row_mask:0xf bank_mask:0xf
	v_fmac_f32_dpp v213, v169, v133 row_shl:15 row_mask:0xf bank_mask:0xf
	v_fmac_f32_dpp v214, v170, v134 row_shl:15 row_mask:0xf bank_mask:0xf
	v_fmac_f32_dpp v215, v171, v135 row_shl:15 row_mask:0xf bank_mask:0xf
	v_fmac_f32_dpp v212, v84, v140 row_shr:15 row_mask:0xf bank_mask:0xf
	v_fmac_f32_dpp v213, v85, v141 row_shr:15 row_mask:0xf bank_mask:0xf
	v_fmac_f32_dpp v214, v86, v142 row_shr:15 row_mask:0xf bank_mask:0xf
	v_fmac_f32_dpp v215, v87, v143 row_shr:15 row_mask:0xf bank_mask:0xf
	ds_read_b128 v[164:167], v223 offset:0
	ds_read_b128 v[168:171], v223 offset:512
	v_pk_mul_f32 v[216:217], v[208:209], v[224:225] op_sel_hi:[1,0]
	v_pk_mul_f32 v[218:219], v[210:211], v[224:225] op_sel_hi:[1,0]
	v_exp_f32_e32 v216, v216
	v_exp_f32_e32 v217, v217
	v_exp_f32_e32 v218, v218
	v_exp_f32_e32 v219, v219
	v_pk_add_f32 v[216:217], v[216:217], 1.0 op_sel_hi:[1,0]
	v_pk_add_f32 v[218:219], v[218:219], 1.0 op_sel_hi:[1,0]
	v_rcp_f32_e32 v216, v216
	v_rcp_f32_e32 v217, v217
	v_rcp_f32_e32 v218, v218
	v_rcp_f32_e32 v219, v219
	v_pk_mul_f32 v[208:209], v[208:209], v[216:217]
	v_pk_mul_f32 v[210:211], v[210:211], v[218:219]
	v_pk_mul_f32 v[208:209], v[208:209], v[212:213]
	v_pk_mul_f32 v[210:211], v[210:211], v[214:215]
	v_cvt_pk_bf16_f32 v242, v208, v209
	v_cvt_pk_bf16_f32 v243, v210, v211
	s_waitcnt lgkmcnt(0)
	v_pk_fma_f32 v[208:209], v[120:121], v[68:69], v[128:129]
	v_pk_fma_f32 v[210:211], v[122:123], v[70:71], v[130:131]
	v_fmac_f32_dpp v208, v68, v116 row_shr:1 row_mask:0xf bank_mask:0xf
	v_fmac_f32_dpp v209, v69, v117 row_shr:1 row_mask:0xf bank_mask:0xf
	v_fmac_f32_dpp v210, v70, v118 row_shr:1 row_mask:0xf bank_mask:0xf
	v_fmac_f32_dpp v211, v71, v119 row_shr:1 row_mask:0xf bank_mask:0xf
	v_fmac_f32_dpp v208, v68, v124 row_shl:1 row_mask:0xf bank_mask:0xf
	v_fmac_f32_dpp v209, v69, v125 row_shl:1 row_mask:0xf bank_mask:0xf
	v_fmac_f32_dpp v210, v70, v126 row_shl:1 row_mask:0xf bank_mask:0xf
	v_fmac_f32_dpp v211, v71, v127 row_shl:1 row_mask:0xf bank_mask:0xf
	v_fmac_f32_dpp v208, v80, v116 row_shl:15 row_mask:0xf bank_mask:0xf
	v_fmac_f32_dpp v209, v81, v117 row_shl:15 row_mask:0xf bank_mask:0xf
	v_fmac_f32_dpp v210, v82, v118 row_shl:15 row_mask:0xf bank_mask:0xf
	v_fmac_f32_dpp v211, v83, v119 row_shl:15 row_mask:0xf bank_mask:0xf
	v_fmac_f32_dpp v208, v164, v124 row_shr:15 row_mask:0xf bank_mask:0xf
	v_fmac_f32_dpp v209, v165, v125 row_shr:15 row_mask:0xf bank_mask:0xf
	v_fmac_f32_dpp v210, v166, v126 row_shr:15 row_mask:0xf bank_mask:0xf
	v_fmac_f32_dpp v211, v167, v127 row_shr:15 row_mask:0xf bank_mask:0xf
	v_pk_fma_f32 v[212:213], v[136:137], v[72:73], v[144:145]
	v_pk_fma_f32 v[214:215], v[138:139], v[74:75], v[146:147]
	v_fmac_f32_dpp v212, v72, v132 row_shr:1 row_mask:0xf bank_mask:0xf
	v_fmac_f32_dpp v213, v73, v133 row_shr:1 row_mask:0xf bank_mask:0xf
	v_fmac_f32_dpp v214, v74, v134 row_shr:1 row_mask:0xf bank_mask:0xf
	v_fmac_f32_dpp v215, v75, v135 row_shr:1 row_mask:0xf bank_mask:0xf
	v_fmac_f32_dpp v212, v72, v140 row_shl:1 row_mask:0xf bank_mask:0xf
	v_fmac_f32_dpp v213, v73, v141 row_shl:1 row_mask:0xf bank_mask:0xf
	v_fmac_f32_dpp v214, v74, v142 row_shl:1 row_mask:0xf bank_mask:0xf
	v_fmac_f32_dpp v215, v75, v143 row_shl:1 row_mask:0xf bank_mask:0xf
	v_fmac_f32_dpp v212, v76, v132 row_shl:15 row_mask:0xf bank_mask:0xf
	v_fmac_f32_dpp v213, v77, v133 row_shl:15 row_mask:0xf bank_mask:0xf
	v_fmac_f32_dpp v214, v78, v134 row_shl:15 row_mask:0xf bank_mask:0xf
	v_fmac_f32_dpp v215, v79, v135 row_shl:15 row_mask:0xf bank_mask:0xf
	v_fmac_f32_dpp v212, v168, v140 row_shr:15 row_mask:0xf bank_mask:0xf
	v_fmac_f32_dpp v213, v169, v141 row_shr:15 row_mask:0xf bank_mask:0xf
	v_fmac_f32_dpp v214, v170, v142 row_shr:15 row_mask:0xf bank_mask:0xf
	v_fmac_f32_dpp v215, v171, v143 row_shr:15 row_mask:0xf bank_mask:0xf
	v_pk_mul_f32 v[216:217], v[208:209], v[224:225] op_sel_hi:[1,0]
	v_pk_mul_f32 v[218:219], v[210:211], v[224:225] op_sel_hi:[1,0]
	v_exp_f32_e32 v216, v216
	v_exp_f32_e32 v217, v217
	v_exp_f32_e32 v218, v218
	v_exp_f32_e32 v219, v219
	v_pk_add_f32 v[216:217], v[216:217], 1.0 op_sel_hi:[1,0]
	v_pk_add_f32 v[218:219], v[218:219], 1.0 op_sel_hi:[1,0]
	v_rcp_f32_e32 v216, v216
	v_rcp_f32_e32 v217, v217
	v_rcp_f32_e32 v218, v218
	v_rcp_f32_e32 v219, v219
	v_pk_mul_f32 v[208:209], v[208:209], v[216:217]
	v_pk_mul_f32 v[210:211], v[210:211], v[218:219]
	v_pk_mul_f32 v[208:209], v[208:209], v[212:213]
	v_pk_mul_f32 v[210:211], v[210:211], v[214:215]
	v_cvt_pk_bf16_f32 v206, v208, v209
	v_cvt_pk_bf16_f32 v207, v210, v211
	ds_read_b128 v[164:167], v222 offset:16
	ds_read_b128 v[168:171], v222 offset:528
	s_waitcnt vmcnt(0)
	v_pk_fma_f32 v[208:209], v[152:153], v[56:57], v[100:101]
	v_pk_fma_f32 v[210:211], v[154:155], v[58:59], v[102:103]
	v_fmac_f32_dpp v208, v56, v160 row_shr:1 row_mask:0xf bank_mask:0xf
	v_fmac_f32_dpp v209, v57, v161 row_shr:1 row_mask:0xf bank_mask:0xf
	v_fmac_f32_dpp v210, v58, v162 row_shr:1 row_mask:0xf bank_mask:0xf
	v_fmac_f32_dpp v211, v59, v163 row_shr:1 row_mask:0xf bank_mask:0xf
	v_fmac_f32_dpp v208, v56, v112 row_shl:1 row_mask:0xf bank_mask:0xf
	v_fmac_f32_dpp v209, v57, v113 row_shl:1 row_mask:0xf bank_mask:0xf
	v_fmac_f32_dpp v210, v58, v114 row_shl:1 row_mask:0xf bank_mask:0xf
	v_fmac_f32_dpp v211, v59, v115 row_shl:1 row_mask:0xf bank_mask:0xf
	v_fmac_f32_dpp v208, v64, v160 row_shl:15 row_mask:0xf bank_mask:0xf
	v_fmac_f32_dpp v209, v65, v161 row_shl:15 row_mask:0xf bank_mask:0xf
	v_fmac_f32_dpp v210, v66, v162 row_shl:15 row_mask:0xf bank_mask:0xf
	v_fmac_f32_dpp v211, v67, v163 row_shl:15 row_mask:0xf bank_mask:0xf
	v_fmac_f32_dpp v208, v48, v112 row_shr:15 row_mask:0xf bank_mask:0xf
	v_fmac_f32_dpp v209, v49, v113 row_shr:15 row_mask:0xf bank_mask:0xf
	v_fmac_f32_dpp v210, v50, v114 row_shr:15 row_mask:0xf bank_mask:0xf
	v_fmac_f32_dpp v211, v51, v115 row_shr:15 row_mask:0xf bank_mask:0xf
	v_pk_fma_f32 v[212:213], v[148:149], v[52:53], v[104:105]
	v_pk_fma_f32 v[214:215], v[150:151], v[54:55], v[106:107]
	v_fmac_f32_dpp v212, v52, v156 row_shr:1 row_mask:0xf bank_mask:0xf
	v_fmac_f32_dpp v213, v53, v157 row_shr:1 row_mask:0xf bank_mask:0xf
	v_fmac_f32_dpp v214, v54, v158 row_shr:1 row_mask:0xf bank_mask:0xf
	v_fmac_f32_dpp v215, v55, v159 row_shr:1 row_mask:0xf bank_mask:0xf
	v_fmac_f32_dpp v212, v52, v108 row_shl:1 row_mask:0xf bank_mask:0xf
	v_fmac_f32_dpp v213, v53, v109 row_shl:1 row_mask:0xf bank_mask:0xf
	v_fmac_f32_dpp v214, v54, v110 row_shl:1 row_mask:0xf bank_mask:0xf
	v_fmac_f32_dpp v215, v55, v111 row_shl:1 row_mask:0xf bank_mask:0xf
	v_fmac_f32_dpp v212, v60, v156 row_shl:15 row_mask:0xf bank_mask:0xf
	v_fmac_f32_dpp v213, v61, v157 row_shl:15 row_mask:0xf bank_mask:0xf
	v_fmac_f32_dpp v214, v62, v158 row_shl:15 row_mask:0xf bank_mask:0xf
	v_fmac_f32_dpp v215, v63, v159 row_shl:15 row_mask:0xf bank_mask:0xf
	v_fmac_f32_dpp v212, v44, v108 row_shr:15 row_mask:0xf bank_mask:0xf
	v_fmac_f32_dpp v213, v45, v109 row_shr:15 row_mask:0xf bank_mask:0xf
	v_fmac_f32_dpp v214, v46, v110 row_shr:15 row_mask:0xf bank_mask:0xf
	v_fmac_f32_dpp v215, v47, v111 row_shr:15 row_mask:0xf bank_mask:0xf
	v_pk_mul_f32 v[216:217], v[208:209], v[224:225] op_sel_hi:[1,0]
	v_pk_mul_f32 v[218:219], v[210:211], v[224:225] op_sel_hi:[1,0]
	v_exp_f32_e32 v216, v216
	v_exp_f32_e32 v217, v217
	v_exp_f32_e32 v218, v218
	v_exp_f32_e32 v219, v219
	v_pk_add_f32 v[216:217], v[216:217], 1.0 op_sel_hi:[1,0]
	v_pk_add_f32 v[218:219], v[218:219], 1.0 op_sel_hi:[1,0]
	v_rcp_f32_e32 v216, v216
	v_rcp_f32_e32 v217, v217
	v_rcp_f32_e32 v218, v218
	v_rcp_f32_e32 v219, v219
	v_pk_mul_f32 v[208:209], v[208:209], v[216:217]
	v_pk_mul_f32 v[210:211], v[210:211], v[218:219]
	v_pk_mul_f32 v[208:209], v[208:209], v[212:213]
	v_pk_mul_f32 v[210:211], v[210:211], v[214:215]
	v_cvt_pk_bf16_f32 v118, v208, v209
	v_cvt_pk_bf16_f32 v119, v210, v211
	v_mov_b32_e32 v116, v174
	v_mov_b32_e32 v117, v175
	s_add_u32 s4, s6, 0x16000
	s_addc_u32 s5, s7, 0
	global_store_dwordx4 v244, v[116:119], s[4:5] sc1
	v_pk_fma_f32 v[208:209], v[152:153], v[48:49], v[100:101]
	v_pk_fma_f32 v[210:211], v[154:155], v[50:51], v[102:103]
	v_fmac_f32_dpp v208, v48, v160 row_shr:1 row_mask:0xf bank_mask:0xf
	v_fmac_f32_dpp v209, v49, v161 row_shr:1 row_mask:0xf bank_mask:0xf
	v_fmac_f32_dpp v210, v50, v162 row_shr:1 row_mask:0xf bank_mask:0xf
	v_fmac_f32_dpp v211, v51, v163 row_shr:1 row_mask:0xf bank_mask:0xf
	v_fmac_f32_dpp v208, v48, v112 row_shl:1 row_mask:0xf bank_mask:0xf
	v_fmac_f32_dpp v209, v49, v113 row_shl:1 row_mask:0xf bank_mask:0xf
	v_fmac_f32_dpp v210, v50, v114 row_shl:1 row_mask:0xf bank_mask:0xf
	v_fmac_f32_dpp v211, v51, v115 row_shl:1 row_mask:0xf bank_mask:0xf
	v_fmac_f32_dpp v208, v56, v160 row_shl:15 row_mask:0xf bank_mask:0xf
	v_fmac_f32_dpp v209, v57, v161 row_shl:15 row_mask:0xf bank_mask:0xf
	v_fmac_f32_dpp v210, v58, v162 row_shl:15 row_mask:0xf bank_mask:0xf
	v_fmac_f32_dpp v211, v59, v163 row_shl:15 row_mask:0xf bank_mask:0xf
	v_fmac_f32_dpp v208, v36, v112 row_shr:15 row_mask:0xf bank_mask:0xf
	v_fmac_f32_dpp v209, v37, v113 row_shr:15 row_mask:0xf bank_mask:0xf
	v_fmac_f32_dpp v210, v38, v114 row_shr:15 row_mask:0xf bank_mask:0xf
	v_fmac_f32_dpp v211, v39, v115 row_shr:15 row_mask:0xf bank_mask:0xf
	v_pk_fma_f32 v[212:213], v[148:149], v[44:45], v[104:105]
	v_pk_fma_f32 v[214:215], v[150:151], v[46:47], v[106:107]
	v_fmac_f32_dpp v212, v44, v156 row_shr:1 row_mask:0xf bank_mask:0xf
	v_fmac_f32_dpp v213, v45, v157 row_shr:1 row_mask:0xf bank_mask:0xf
	v_fmac_f32_dpp v214, v46, v158 row_shr:1 row_mask:0xf bank_mask:0xf
	v_fmac_f32_dpp v215, v47, v159 row_shr:1 row_mask:0xf bank_mask:0xf
	v_fmac_f32_dpp v212, v44, v108 row_shl:1 row_mask:0xf bank_mask:0xf
	v_fmac_f32_dpp v213, v45, v109 row_shl:1 row_mask:0xf bank_mask:0xf
	v_fmac_f32_dpp v214, v46, v110 row_shl:1 row_mask:0xf bank_mask:0xf
	v_fmac_f32_dpp v215, v47, v111 row_shl:1 row_mask:0xf bank_mask:0xf
	v_fmac_f32_dpp v212, v52, v156 row_shl:15 row_mask:0xf bank_mask:0xf
	v_fmac_f32_dpp v213, v53, v157 row_shl:15 row_mask:0xf bank_mask:0xf
	v_fmac_f32_dpp v214, v54, v158 row_shl:15 row_mask:0xf bank_mask:0xf
	v_fmac_f32_dpp v215, v55, v159 row_shl:15 row_mask:0xf bank_mask:0xf
	v_fmac_f32_dpp v212, v40, v108 row_shr:15 row_mask:0xf bank_mask:0xf
	v_fmac_f32_dpp v213, v41, v109 row_shr:15 row_mask:0xf bank_mask:0xf
	v_fmac_f32_dpp v214, v42, v110 row_shr:15 row_mask:0xf bank_mask:0xf
	v_fmac_f32_dpp v215, v43, v111 row_shr:15 row_mask:0xf bank_mask:0xf
	v_pk_mul_f32 v[216:217], v[208:209], v[224:225] op_sel_hi:[1,0]
	v_pk_mul_f32 v[218:219], v[210:211], v[224:225] op_sel_hi:[1,0]
	v_exp_f32_e32 v216, v216
	v_exp_f32_e32 v217, v217
	v_exp_f32_e32 v218, v218
	v_exp_f32_e32 v219, v219
	v_pk_add_f32 v[216:217], v[216:217], 1.0 op_sel_hi:[1,0]
	v_pk_add_f32 v[218:219], v[218:219], 1.0 op_sel_hi:[1,0]
	v_rcp_f32_e32 v216, v216
	v_rcp_f32_e32 v217, v217
	v_rcp_f32_e32 v218, v218
	v_rcp_f32_e32 v219, v219
	v_pk_mul_f32 v[208:209], v[208:209], v[216:217]
	v_pk_mul_f32 v[210:211], v[210:211], v[218:219]
	v_pk_mul_f32 v[208:209], v[208:209], v[212:213]
	v_pk_mul_f32 v[210:211], v[210:211], v[214:215]
	v_cvt_pk_bf16_f32 v122, v208, v209
	v_cvt_pk_bf16_f32 v123, v210, v211
	v_mov_b32_e32 v120, v176
	v_mov_b32_e32 v121, v177
	s_add_u32 s4, s6, 0x2c000
	s_addc_u32 s5, s7, 0
	global_store_dwordx4 v244, v[120:123], s[4:5] sc1
	s_waitcnt lgkmcnt(0)
	v_pk_fma_f32 v[208:209], v[152:153], v[64:65], v[100:101]
	v_pk_fma_f32 v[210:211], v[154:155], v[66:67], v[102:103]
	v_fmac_f32_dpp v208, v64, v160 row_shr:1 row_mask:0xf bank_mask:0xf
	v_fmac_f32_dpp v209, v65, v161 row_shr:1 row_mask:0xf bank_mask:0xf
	v_fmac_f32_dpp v210, v66, v162 row_shr:1 row_mask:0xf bank_mask:0xf
	v_fmac_f32_dpp v211, v67, v163 row_shr:1 row_mask:0xf bank_mask:0xf
	v_fmac_f32_dpp v208, v64, v112 row_shl:1 row_mask:0xf bank_mask:0xf
	v_fmac_f32_dpp v209, v65, v113 row_shl:1 row_mask:0xf bank_mask:0xf
	v_fmac_f32_dpp v210, v66, v114 row_shl:1 row_mask:0xf bank_mask:0xf
	v_fmac_f32_dpp v211, v67, v115 row_shl:1 row_mask:0xf bank_mask:0xf
	v_fmac_f32_dpp v208, v164, v160 row_shl:15 row_mask:0xf bank_mask:0xf
	v_fmac_f32_dpp v209, v165, v161 row_shl:15 row_mask:0xf bank_mask:0xf
	v_fmac_f32_dpp v210, v166, v162 row_shl:15 row_mask:0xf bank_mask:0xf
	v_fmac_f32_dpp v211, v167, v163 row_shl:15 row_mask:0xf bank_mask:0xf
	v_fmac_f32_dpp v208, v56, v112 row_shr:15 row_mask:0xf bank_mask:0xf
	v_fmac_f32_dpp v209, v57, v113 row_shr:15 row_mask:0xf bank_mask:0xf
	v_fmac_f32_dpp v210, v58, v114 row_shr:15 row_mask:0xf bank_mask:0xf
	v_fmac_f32_dpp v211, v59, v115 row_shr:15 row_mask:0xf bank_mask:0xf
	v_pk_fma_f32 v[212:213], v[148:149], v[60:61], v[104:105]
	v_pk_fma_f32 v[214:215], v[150:151], v[62:63], v[106:107]
	v_fmac_f32_dpp v212, v60, v156 row_shr:1 row_mask:0xf bank_mask:0xf
	v_fmac_f32_dpp v213, v61, v157 row_shr:1 row_mask:0xf bank_mask:0xf
	v_fmac_f32_dpp v214, v62, v158 row_shr:1 row_mask:0xf bank_mask:0xf
	v_fmac_f32_dpp v215, v63, v159 row_shr:1 row_mask:0xf bank_mask:0xf
	v_fmac_f32_dpp v212, v60, v108 row_shl:1 row_mask:0xf bank_mask:0xf
	v_fmac_f32_dpp v213, v61, v109 row_shl:1 row_mask:0xf bank_mask:0xf
	v_fmac_f32_dpp v214, v62, v110 row_shl:1 row_mask:0xf bank_mask:0xf
	v_fmac_f32_dpp v215, v63, v111 row_shl:1 row_mask:0xf bank_mask:0xf
	v_fmac_f32_dpp v212, v168, v156 row_shl:15 row_mask:0xf bank_mask:0xf
	v_fmac_f32_dpp v213, v169, v157 row_shl:15 row_mask:0xf bank_mask:0xf
	v_fmac_f32_dpp v214, v170, v158 row_shl:15 row_mask:0xf bank_mask:0xf
	v_fmac_f32_dpp v215, v171, v159 row_shl:15 row_mask:0xf bank_mask:0xf
	v_fmac_f32_dpp v212, v52, v108 row_shr:15 row_mask:0xf bank_mask:0xf
	v_fmac_f32_dpp v213, v53, v109 row_shr:15 row_mask:0xf bank_mask:0xf
	v_fmac_f32_dpp v214, v54, v110 row_shr:15 row_mask:0xf bank_mask:0xf
	v_fmac_f32_dpp v215, v55, v111 row_shr:15 row_mask:0xf bank_mask:0xf
	ds_read_b128 v[164:167], v221 offset:2064
	ds_read_b128 v[168:171], v221 offset:2576
	v_pk_mul_f32 v[216:217], v[208:209], v[224:225] op_sel_hi:[1,0]
	v_pk_mul_f32 v[218:219], v[210:211], v[224:225] op_sel_hi:[1,0]
	v_exp_f32_e32 v216, v216
	v_exp_f32_e32 v217, v217
	v_exp_f32_e32 v218, v218
	v_exp_f32_e32 v219, v219
	v_pk_add_f32 v[216:217], v[216:217], 1.0 op_sel_hi:[1,0]
	v_pk_add_f32 v[218:219], v[218:219], 1.0 op_sel_hi:[1,0]
	v_rcp_f32_e32 v216, v216
	v_rcp_f32_e32 v217, v217
	v_rcp_f32_e32 v218, v218
	v_rcp_f32_e32 v219, v219
	v_pk_mul_f32 v[208:209], v[208:209], v[216:217]
	v_pk_mul_f32 v[210:211], v[210:211], v[218:219]
	v_pk_mul_f32 v[208:209], v[208:209], v[212:213]
	v_pk_mul_f32 v[210:211], v[210:211], v[214:215]
	v_cvt_pk_bf16_f32 v118, v208, v209
	v_cvt_pk_bf16_f32 v119, v210, v211
	v_mov_b32_e32 v116, v172
	v_mov_b32_e32 v117, v173
	s_cmp_eq_u32 s98, 0
	s_cselect_b32 s99, 0xfffefffe, -1
	s_mov_b32 exec_lo, s99
	s_mov_b32 exec_hi, s99
	global_store_dwordx4 v244, v[116:119], s[6:7] sc1
	s_mov_b64 exec, -1
	s_waitcnt lgkmcnt(0)
	v_pk_fma_f32 v[208:209], v[152:153], v[36:37], v[100:101]
	v_pk_fma_f32 v[210:211], v[154:155], v[38:39], v[102:103]
	v_fmac_f32_dpp v208, v36, v160 row_shr:1 row_mask:0xf bank_mask:0xf
	v_fmac_f32_dpp v209, v37, v161 row_shr:1 row_mask:0xf bank_mask:0xf
	v_fmac_f32_dpp v210, v38, v162 row_shr:1 row_mask:0xf bank_mask:0xf
	v_fmac_f32_dpp v211, v39, v163 row_shr:1 row_mask:0xf bank_mask:0xf
	v_fmac_f32_dpp v208, v36, v112 row_shl:1 row_mask:0xf bank_mask:0xf
	v_fmac_f32_dpp v209, v37, v113 row_shl:1 row_mask:0xf bank_mask:0xf
	v_fmac_f32_dpp v210, v38, v114 row_shl:1 row_mask:0xf bank_mask:0xf
	v_fmac_f32_dpp v211, v39, v115 row_shl:1 row_mask:0xf bank_mask:0xf
	v_fmac_f32_dpp v208, v48, v160 row_shl:15 row_mask:0xf bank_mask:0xf
	v_fmac_f32_dpp v209, v49, v161 row_shl:15 row_mask:0xf bank_mask:0xf
	v_fmac_f32_dpp v210, v50, v162 row_shl:15 row_mask:0xf bank_mask:0xf
	v_fmac_f32_dpp v211, v51, v163 row_shl:15 row_mask:0xf bank_mask:0xf
	v_fmac_f32_dpp v208, v164, v112 row_shr:15 row_mask:0xf bank_mask:0xf
	v_fmac_f32_dpp v209, v165, v113 row_shr:15 row_mask:0xf bank_mask:0xf
	v_fmac_f32_dpp v210, v166, v114 row_shr:15 row_mask:0xf bank_mask:0xf
	v_fmac_f32_dpp v211, v167, v115 row_shr:15 row_mask:0xf bank_mask:0xf
	v_pk_fma_f32 v[212:213], v[148:149], v[40:41], v[104:105]
	v_pk_fma_f32 v[214:215], v[150:151], v[42:43], v[106:107]
	v_fmac_f32_dpp v212, v40, v156 row_shr:1 row_mask:0xf bank_mask:0xf
	v_fmac_f32_dpp v213, v41, v157 row_shr:1 row_mask:0xf bank_mask:0xf
	v_fmac_f32_dpp v214, v42, v158 row_shr:1 row_mask:0xf bank_mask:0xf
	v_fmac_f32_dpp v215, v43, v159 row_shr:1 row_mask:0xf bank_mask:0xf
	v_fmac_f32_dpp v212, v40, v108 row_shl:1 row_mask:0xf bank_mask:0xf
	v_fmac_f32_dpp v213, v41, v109 row_shl:1 row_mask:0xf bank_mask:0xf
	v_fmac_f32_dpp v214, v42, v110 row_shl:1 row_mask:0xf bank_mask:0xf
	v_fmac_f32_dpp v215, v43, v111 row_shl:1 row_mask:0xf bank_mask:0xf
	v_fmac_f32_dpp v212, v44, v156 row_shl:15 row_mask:0xf bank_mask:0xf
	v_fmac_f32_dpp v213, v45, v157 row_shl:15 row_mask:0xf bank_mask:0xf
	v_fmac_f32_dpp v214, v46, v158 row_shl:15 row_mask:0xf bank_mask:0xf
	v_fmac_f32_dpp v215, v47, v159 row_shl:15 row_mask:0xf bank_mask:0xf
	v_fmac_f32_dpp v212, v168, v108 row_shr:15 row_mask:0xf bank_mask:0xf
	v_fmac_f32_dpp v213, v169, v109 row_shr:15 row_mask:0xf bank_mask:0xf
	v_fmac_f32_dpp v214, v170, v110 row_shr:15 row_mask:0xf bank_mask:0xf
	v_fmac_f32_dpp v215, v171, v111 row_shr:15 row_mask:0xf bank_mask:0xf
	v_pk_mul_f32 v[216:217], v[208:209], v[224:225] op_sel_hi:[1,0]
	v_pk_mul_f32 v[218:219], v[210:211], v[224:225] op_sel_hi:[1,0]
	v_exp_f32_e32 v216, v216
	v_exp_f32_e32 v217, v217
	v_exp_f32_e32 v218, v218
	v_exp_f32_e32 v219, v219
	v_pk_add_f32 v[216:217], v[216:217], 1.0 op_sel_hi:[1,0]
	v_pk_add_f32 v[218:219], v[218:219], 1.0 op_sel_hi:[1,0]
	v_rcp_f32_e32 v216, v216
	v_rcp_f32_e32 v217, v217
	v_rcp_f32_e32 v218, v218
	v_rcp_f32_e32 v219, v219
	v_pk_mul_f32 v[208:209], v[208:209], v[216:217]
	v_pk_mul_f32 v[210:211], v[210:211], v[218:219]
	v_pk_mul_f32 v[208:209], v[208:209], v[212:213]
	v_pk_mul_f32 v[210:211], v[210:211], v[214:215]
	v_cvt_pk_bf16_f32 v122, v208, v209
	v_cvt_pk_bf16_f32 v123, v210, v211
	v_mov_b32_e32 v120, v178
	v_mov_b32_e32 v121, v179
	s_add_u32 s4, s6, 0x42000
	s_addc_u32 s5, s7, 0
	global_store_dwordx4 v244, v[120:123], s[4:5] sc1
	ds_read_b128 v[164:167], v221 offset:3088
	ds_read_b128 v[168:171], v221 offset:3600
	v_pk_fma_f32 v[208:209], v[152:153], v[24:25], v[100:101]
	v_pk_fma_f32 v[210:211], v[154:155], v[26:27], v[102:103]
	v_fmac_f32_dpp v208, v24, v160 row_shr:1 row_mask:0xf bank_mask:0xf
	v_fmac_f32_dpp v209, v25, v161 row_shr:1 row_mask:0xf bank_mask:0xf
	v_fmac_f32_dpp v210, v26, v162 row_shr:1 row_mask:0xf bank_mask:0xf
	v_fmac_f32_dpp v211, v27, v163 row_shr:1 row_mask:0xf bank_mask:0xf
	v_fmac_f32_dpp v208, v24, v112 row_shl:1 row_mask:0xf bank_mask:0xf
	v_fmac_f32_dpp v209, v25, v113 row_shl:1 row_mask:0xf bank_mask:0xf
	v_fmac_f32_dpp v210, v26, v114 row_shl:1 row_mask:0xf bank_mask:0xf
	v_fmac_f32_dpp v211, v27, v115 row_shl:1 row_mask:0xf bank_mask:0xf
	v_fmac_f32_dpp v208, v32, v160 row_shl:15 row_mask:0xf bank_mask:0xf
	v_fmac_f32_dpp v209, v33, v161 row_shl:15 row_mask:0xf bank_mask:0xf
	v_fmac_f32_dpp v210, v34, v162 row_shl:15 row_mask:0xf bank_mask:0xf
	v_fmac_f32_dpp v211, v35, v163 row_shl:15 row_mask:0xf bank_mask:0xf
	v_fmac_f32_dpp v208, v16, v112 row_shr:15 row_mask:0xf bank_mask:0xf
	v_fmac_f32_dpp v209, v17, v113 row_shr:15 row_mask:0xf bank_mask:0xf
	v_fmac_f32_dpp v210, v18, v114 row_shr:15 row_mask:0xf bank_mask:0xf
	v_fmac_f32_dpp v211, v19, v115 row_shr:15 row_mask:0xf bank_mask:0xf
	v_pk_fma_f32 v[212:213], v[148:149], v[20:21], v[104:105]
	v_pk_fma_f32 v[214:215], v[150:151], v[22:23], v[106:107]
	v_fmac_f32_dpp v212, v20, v156 row_shr:1 row_mask:0xf bank_mask:0xf
	v_fmac_f32_dpp v213, v21, v157 row_shr:1 row_mask:0xf bank_mask:0xf
	v_fmac_f32_dpp v214, v22, v158 row_shr:1 row_mask:0xf bank_mask:0xf
	v_fmac_f32_dpp v215, v23, v159 row_shr:1 row_mask:0xf bank_mask:0xf
	v_fmac_f32_dpp v212, v20, v108 row_shl:1 row_mask:0xf bank_mask:0xf
	v_fmac_f32_dpp v213, v21, v109 row_shl:1 row_mask:0xf bank_mask:0xf
	v_fmac_f32_dpp v214, v22, v110 row_shl:1 row_mask:0xf bank_mask:0xf
	v_fmac_f32_dpp v215, v23, v111 row_shl:1 row_mask:0xf bank_mask:0xf
	v_fmac_f32_dpp v212, v28, v156 row_shl:15 row_mask:0xf bank_mask:0xf
	v_fmac_f32_dpp v213, v29, v157 row_shl:15 row_mask:0xf bank_mask:0xf
	v_fmac_f32_dpp v214, v30, v158 row_shl:15 row_mask:0xf bank_mask:0xf
	v_fmac_f32_dpp v215, v31, v159 row_shl:15 row_mask:0xf bank_mask:0xf
	v_fmac_f32_dpp v212, v12, v108 row_shr:15 row_mask:0xf bank_mask:0xf
	v_fmac_f32_dpp v213, v13, v109 row_shr:15 row_mask:0xf bank_mask:0xf
	v_fmac_f32_dpp v214, v14, v110 row_shr:15 row_mask:0xf bank_mask:0xf
	v_fmac_f32_dpp v215, v15, v111 row_shr:15 row_mask:0xf bank_mask:0xf
	v_pk_mul_f32 v[216:217], v[208:209], v[224:225] op_sel_hi:[1,0]
	v_pk_mul_f32 v[218:219], v[210:211], v[224:225] op_sel_hi:[1,0]
	v_exp_f32_e32 v216, v216
	v_exp_f32_e32 v217, v217
	v_exp_f32_e32 v218, v218
	v_exp_f32_e32 v219, v219
	v_pk_add_f32 v[216:217], v[216:217], 1.0 op_sel_hi:[1,0]
	v_pk_add_f32 v[218:219], v[218:219], 1.0 op_sel_hi:[1,0]
	v_rcp_f32_e32 v216, v216
	v_rcp_f32_e32 v217, v217
	v_rcp_f32_e32 v218, v218
	v_rcp_f32_e32 v219, v219
	v_pk_mul_f32 v[208:209], v[208:209], v[216:217]
	v_pk_mul_f32 v[210:211], v[210:211], v[218:219]
	v_pk_mul_f32 v[208:209], v[208:209], v[212:213]
	v_pk_mul_f32 v[210:211], v[210:211], v[214:215]
	v_cvt_pk_bf16_f32 v118, v208, v209
	v_cvt_pk_bf16_f32 v119, v210, v211
	v_mov_b32_e32 v116, v247
	v_mov_b32_e32 v117, v248
	s_add_u32 s4, s6, 0xc6000
	s_addc_u32 s5, s7, 0
	global_store_dwordx4 v244, v[116:119], s[4:5] sc1
	v_pk_fma_f32 v[208:209], v[152:153], v[16:17], v[100:101]
	v_pk_fma_f32 v[210:211], v[154:155], v[18:19], v[102:103]
	v_fmac_f32_dpp v208, v16, v160 row_shr:1 row_mask:0xf bank_mask:0xf
	v_fmac_f32_dpp v209, v17, v161 row_shr:1 row_mask:0xf bank_mask:0xf
	v_fmac_f32_dpp v210, v18, v162 row_shr:1 row_mask:0xf bank_mask:0xf
	v_fmac_f32_dpp v211, v19, v163 row_shr:1 row_mask:0xf bank_mask:0xf
	v_fmac_f32_dpp v208, v16, v112 row_shl:1 row_mask:0xf bank_mask:0xf
	v_fmac_f32_dpp v209, v17, v113 row_shl:1 row_mask:0xf bank_mask:0xf
	v_fmac_f32_dpp v210, v18, v114 row_shl:1 row_mask:0xf bank_mask:0xf
	v_fmac_f32_dpp v211, v19, v115 row_shl:1 row_mask:0xf bank_mask:0xf
	v_fmac_f32_dpp v208, v24, v160 row_shl:15 row_mask:0xf bank_mask:0xf
	v_fmac_f32_dpp v209, v25, v161 row_shl:15 row_mask:0xf bank_mask:0xf
	v_fmac_f32_dpp v210, v26, v162 row_shl:15 row_mask:0xf bank_mask:0xf
	v_fmac_f32_dpp v211, v27, v163 row_shl:15 row_mask:0xf bank_mask:0xf
	v_fmac_f32_dpp v208, v4, v112 row_shr:15 row_mask:0xf bank_mask:0xf
	v_fmac_f32_dpp v209, v5, v113 row_shr:15 row_mask:0xf bank_mask:0xf
	v_fmac_f32_dpp v210, v6, v114 row_shr:15 row_mask:0xf bank_mask:0xf
	v_fmac_f32_dpp v211, v7, v115 row_shr:15 row_mask:0xf bank_mask:0xf
	v_pk_fma_f32 v[212:213], v[148:149], v[12:13], v[104:105]
	v_pk_fma_f32 v[214:215], v[150:151], v[14:15], v[106:107]
	v_fmac_f32_dpp v212, v12, v156 row_shr:1 row_mask:0xf bank_mask:0xf
	v_fmac_f32_dpp v213, v13, v157 row_shr:1 row_mask:0xf bank_mask:0xf
	v_fmac_f32_dpp v214, v14, v158 row_shr:1 row_mask:0xf bank_mask:0xf
	v_fmac_f32_dpp v215, v15, v159 row_shr:1 row_mask:0xf bank_mask:0xf
	v_fmac_f32_dpp v212, v12, v108 row_shl:1 row_mask:0xf bank_mask:0xf
	v_fmac_f32_dpp v213, v13, v109 row_shl:1 row_mask:0xf bank_mask:0xf
	v_fmac_f32_dpp v214, v14, v110 row_shl:1 row_mask:0xf bank_mask:0xf
	v_fmac_f32_dpp v215, v15, v111 row_shl:1 row_mask:0xf bank_mask:0xf
	v_fmac_f32_dpp v212, v20, v156 row_shl:15 row_mask:0xf bank_mask:0xf
	v_fmac_f32_dpp v213, v21, v157 row_shl:15 row_mask:0xf bank_mask:0xf
	v_fmac_f32_dpp v214, v22, v158 row_shl:15 row_mask:0xf bank_mask:0xf
	v_fmac_f32_dpp v215, v23, v159 row_shl:15 row_mask:0xf bank_mask:0xf
	v_fmac_f32_dpp v212, v8, v108 row_shr:15 row_mask:0xf bank_mask:0xf
	v_fmac_f32_dpp v213, v9, v109 row_shr:15 row_mask:0xf bank_mask:0xf
	v_fmac_f32_dpp v214, v10, v110 row_shr:15 row_mask:0xf bank_mask:0xf
	v_fmac_f32_dpp v215, v11, v111 row_shr:15 row_mask:0xf bank_mask:0xf
	v_pk_mul_f32 v[216:217], v[208:209], v[224:225] op_sel_hi:[1,0]
	v_pk_mul_f32 v[218:219], v[210:211], v[224:225] op_sel_hi:[1,0]
	v_exp_f32_e32 v216, v216
	v_exp_f32_e32 v217, v217
	v_exp_f32_e32 v218, v218
	v_exp_f32_e32 v219, v219
	v_pk_add_f32 v[216:217], v[216:217], 1.0 op_sel_hi:[1,0]
	v_pk_add_f32 v[218:219], v[218:219], 1.0 op_sel_hi:[1,0]
	v_rcp_f32_e32 v216, v216
	v_rcp_f32_e32 v217, v217
	v_rcp_f32_e32 v218, v218
	v_rcp_f32_e32 v219, v219
	v_pk_mul_f32 v[208:209], v[208:209], v[216:217]
	v_pk_mul_f32 v[210:211], v[210:211], v[218:219]
	v_pk_mul_f32 v[208:209], v[208:209], v[212:213]
	v_pk_mul_f32 v[210:211], v[210:211], v[214:215]
	v_cvt_pk_bf16_f32 v122, v208, v209
	v_cvt_pk_bf16_f32 v123, v210, v211
	v_mov_b32_e32 v120, v249
	v_mov_b32_e32 v121, v2
	s_add_u32 s4, s6, 0xdc000
	s_addc_u32 s5, s7, 0
	global_store_dwordx4 v244, v[120:123], s[4:5] sc1
	s_waitcnt lgkmcnt(0)
	v_pk_fma_f32 v[208:209], v[152:153], v[32:33], v[100:101]
	v_pk_fma_f32 v[210:211], v[154:155], v[34:35], v[102:103]
	v_fmac_f32_dpp v208, v32, v160 row_shr:1 row_mask:0xf bank_mask:0xf
	v_fmac_f32_dpp v209, v33, v161 row_shr:1 row_mask:0xf bank_mask:0xf
	v_fmac_f32_dpp v210, v34, v162 row_shr:1 row_mask:0xf bank_mask:0xf
	v_fmac_f32_dpp v211, v35, v163 row_shr:1 row_mask:0xf bank_mask:0xf
	v_fmac_f32_dpp v208, v32, v112 row_shl:1 row_mask:0xf bank_mask:0xf
	v_fmac_f32_dpp v209, v33, v113 row_shl:1 row_mask:0xf bank_mask:0xf
	v_fmac_f32_dpp v210, v34, v114 row_shl:1 row_mask:0xf bank_mask:0xf
	v_fmac_f32_dpp v211, v35, v115 row_shl:1 row_mask:0xf bank_mask:0xf
	v_fmac_f32_dpp v208, v164, v160 row_shl:15 row_mask:0xf bank_mask:0xf
	v_fmac_f32_dpp v209, v165, v161 row_shl:15 row_mask:0xf bank_mask:0xf
	v_fmac_f32_dpp v210, v166, v162 row_shl:15 row_mask:0xf bank_mask:0xf
	v_fmac_f32_dpp v211, v167, v163 row_shl:15 row_mask:0xf bank_mask:0xf
	v_fmac_f32_dpp v208, v24, v112 row_shr:15 row_mask:0xf bank_mask:0xf
	v_fmac_f32_dpp v209, v25, v113 row_shr:15 row_mask:0xf bank_mask:0xf
	v_fmac_f32_dpp v210, v26, v114 row_shr:15 row_mask:0xf bank_mask:0xf
	v_fmac_f32_dpp v211, v27, v115 row_shr:15 row_mask:0xf bank_mask:0xf
	v_pk_fma_f32 v[212:213], v[148:149], v[28:29], v[104:105]
	v_pk_fma_f32 v[214:215], v[150:151], v[30:31], v[106:107]
	v_fmac_f32_dpp v212, v28, v156 row_shr:1 row_mask:0xf bank_mask:0xf
	v_fmac_f32_dpp v213, v29, v157 row_shr:1 row_mask:0xf bank_mask:0xf
	v_fmac_f32_dpp v214, v30, v158 row_shr:1 row_mask:0xf bank_mask:0xf
	v_fmac_f32_dpp v215, v31, v159 row_shr:1 row_mask:0xf bank_mask:0xf
	v_fmac_f32_dpp v212, v28, v108 row_shl:1 row_mask:0xf bank_mask:0xf
	v_fmac_f32_dpp v213, v29, v109 row_shl:1 row_mask:0xf bank_mask:0xf
	v_fmac_f32_dpp v214, v30, v110 row_shl:1 row_mask:0xf bank_mask:0xf
	v_fmac_f32_dpp v215, v31, v111 row_shl:1 row_mask:0xf bank_mask:0xf
	v_fmac_f32_dpp v212, v168, v156 row_shl:15 row_mask:0xf bank_mask:0xf
	v_fmac_f32_dpp v213, v169, v157 row_shl:15 row_mask:0xf bank_mask:0xf
	v_fmac_f32_dpp v214, v170, v158 row_shl:15 row_mask:0xf bank_mask:0xf
	v_fmac_f32_dpp v215, v171, v159 row_shl:15 row_mask:0xf bank_mask:0xf
	v_fmac_f32_dpp v212, v20, v108 row_shr:15 row_mask:0xf bank_mask:0xf
	v_fmac_f32_dpp v213, v21, v109 row_shr:15 row_mask:0xf bank_mask:0xf
	v_fmac_f32_dpp v214, v22, v110 row_shr:15 row_mask:0xf bank_mask:0xf
	v_fmac_f32_dpp v215, v23, v111 row_shr:15 row_mask:0xf bank_mask:0xf
	ds_read_b128 v[164:167], v223 offset:16
	ds_read_b128 v[168:171], v223 offset:528
	v_pk_mul_f32 v[216:217], v[208:209], v[224:225] op_sel_hi:[1,0]
	v_pk_mul_f32 v[218:219], v[210:211], v[224:225] op_sel_hi:[1,0]
	v_exp_f32_e32 v216, v216
	v_exp_f32_e32 v217, v217
	v_exp_f32_e32 v218, v218
	v_exp_f32_e32 v219, v219
	v_pk_add_f32 v[216:217], v[216:217], 1.0 op_sel_hi:[1,0]
	v_pk_add_f32 v[218:219], v[218:219], 1.0 op_sel_hi:[1,0]
	v_rcp_f32_e32 v216, v216
	v_rcp_f32_e32 v217, v217
	v_rcp_f32_e32 v218, v218
	v_rcp_f32_e32 v219, v219
	v_pk_mul_f32 v[208:209], v[208:209], v[216:217]
	v_pk_mul_f32 v[210:211], v[210:211], v[218:219]
	v_pk_mul_f32 v[208:209], v[208:209], v[212:213]
	v_pk_mul_f32 v[210:211], v[210:211], v[214:215]
	v_cvt_pk_bf16_f32 v118, v208, v209
	v_cvt_pk_bf16_f32 v119, v210, v211
	v_mov_b32_e32 v116, v242
	v_mov_b32_e32 v117, v243
	s_add_u32 s4, s6, 0xb0000
	s_addc_u32 s5, s7, 0
	global_store_dwordx4 v244, v[116:119], s[4:5] sc1
	s_waitcnt lgkmcnt(0)
	v_pk_fma_f32 v[208:209], v[152:153], v[4:5], v[100:101]
	v_pk_fma_f32 v[210:211], v[154:155], v[6:7], v[102:103]
	v_fmac_f32_dpp v208, v4, v160 row_shr:1 row_mask:0xf bank_mask:0xf
	v_fmac_f32_dpp v209, v5, v161 row_shr:1 row_mask:0xf bank_mask:0xf
	v_fmac_f32_dpp v210, v6, v162 row_shr:1 row_mask:0xf bank_mask:0xf
	v_fmac_f32_dpp v211, v7, v163 row_shr:1 row_mask:0xf bank_mask:0xf
	v_fmac_f32_dpp v208, v4, v112 row_shl:1 row_mask:0xf bank_mask:0xf
	v_fmac_f32_dpp v209, v5, v113 row_shl:1 row_mask:0xf bank_mask:0xf
	v_fmac_f32_dpp v210, v6, v114 row_shl:1 row_mask:0xf bank_mask:0xf
	v_fmac_f32_dpp v211, v7, v115 row_shl:1 row_mask:0xf bank_mask:0xf
	v_fmac_f32_dpp v208, v16, v160 row_shl:15 row_mask:0xf bank_mask:0xf
	v_fmac_f32_dpp v209, v17, v161 row_shl:15 row_mask:0xf bank_mask:0xf
	v_fmac_f32_dpp v210, v18, v162 row_shl:15 row_mask:0xf bank_mask:0xf
	v_fmac_f32_dpp v211, v19, v163 row_shl:15 row_mask:0xf bank_mask:0xf
	v_fmac_f32_dpp v208, v164, v112 row_shr:15 row_mask:0xf bank_mask:0xf
	v_fmac_f32_dpp v209, v165, v113 row_shr:15 row_mask:0xf bank_mask:0xf
	v_fmac_f32_dpp v210, v166, v114 row_shr:15 row_mask:0xf bank_mask:0xf
	v_fmac_f32_dpp v211, v167, v115 row_shr:15 row_mask:0xf bank_mask:0xf
	v_pk_fma_f32 v[212:213], v[148:149], v[8:9], v[104:105]
	v_pk_fma_f32 v[214:215], v[150:151], v[10:11], v[106:107]
	v_fmac_f32_dpp v212, v8, v156 row_shr:1 row_mask:0xf bank_mask:0xf
	v_fmac_f32_dpp v213, v9, v157 row_shr:1 row_mask:0xf bank_mask:0xf
	v_fmac_f32_dpp v214, v10, v158 row_shr:1 row_mask:0xf bank_mask:0xf
	v_fmac_f32_dpp v215, v11, v159 row_shr:1 row_mask:0xf bank_mask:0xf
	v_fmac_f32_dpp v212, v8, v108 row_shl:1 row_mask:0xf bank_mask:0xf
	v_fmac_f32_dpp v213, v9, v109 row_shl:1 row_mask:0xf bank_mask:0xf
	v_fmac_f32_dpp v214, v10, v110 row_shl:1 row_mask:0xf bank_mask:0xf
	v_fmac_f32_dpp v215, v11, v111 row_shl:1 row_mask:0xf bank_mask:0xf
	v_fmac_f32_dpp v212, v12, v156 row_shl:15 row_mask:0xf bank_mask:0xf
	v_fmac_f32_dpp v213, v13, v157 row_shl:15 row_mask:0xf bank_mask:0xf
	v_fmac_f32_dpp v214, v14, v158 row_shl:15 row_mask:0xf bank_mask:0xf
	v_fmac_f32_dpp v215, v15, v159 row_shl:15 row_mask:0xf bank_mask:0xf
	v_fmac_f32_dpp v212, v168, v108 row_shr:15 row_mask:0xf bank_mask:0xf
	v_fmac_f32_dpp v213, v169, v109 row_shr:15 row_mask:0xf bank_mask:0xf
	v_fmac_f32_dpp v214, v170, v110 row_shr:15 row_mask:0xf bank_mask:0xf
	v_fmac_f32_dpp v215, v171, v111 row_shr:15 row_mask:0xf bank_mask:0xf
	v_pk_mul_f32 v[216:217], v[208:209], v[224:225] op_sel_hi:[1,0]
	v_pk_mul_f32 v[218:219], v[210:211], v[224:225] op_sel_hi:[1,0]
	v_exp_f32_e32 v216, v216
	v_exp_f32_e32 v217, v217
	v_exp_f32_e32 v218, v218
	v_exp_f32_e32 v219, v219
	v_pk_add_f32 v[216:217], v[216:217], 1.0 op_sel_hi:[1,0]
	v_pk_add_f32 v[218:219], v[218:219], 1.0 op_sel_hi:[1,0]
	v_rcp_f32_e32 v216, v216
	v_rcp_f32_e32 v217, v217
	v_rcp_f32_e32 v218, v218
	v_rcp_f32_e32 v219, v219
	v_pk_mul_f32 v[208:209], v[208:209], v[216:217]
	v_pk_mul_f32 v[210:211], v[210:211], v[218:219]
	v_pk_mul_f32 v[208:209], v[208:209], v[212:213]
	v_pk_mul_f32 v[210:211], v[210:211], v[214:215]
	v_cvt_pk_bf16_f32 v122, v208, v209
	v_cvt_pk_bf16_f32 v123, v210, v211
	v_mov_b32_e32 v120, v206
	v_mov_b32_e32 v121, v207
	s_add_u32 s4, s6, 0xf2000
	s_addc_u32 s5, s7, 0
	s_cmp_eq_u32 s98, 1
	s_cselect_b32 s99, 0x7fff7fff, -1
	s_mov_b32 exec_lo, s99
	s_mov_b32 exec_hi, s99
	global_store_dwordx4 v244, v[120:123], s[4:5] sc1
	s_mov_b64 exec, -1
	s_mov_b64 s[4:5], -1
	s_cmp_eq_u32 s98, 0
	s_cselect_b64 s[8:9], 0, -1
	s_cbranch_scc1 .Lce_nobar1
	s_barrier
